# +E7 sample_state fronts/tails: operand loads issued before the first wait, weight+gate loads together; +E8 gated-delta sample front: conv-buffer and 4 conv-weight loads in one batch; +E3 gd_prep conv4
# speedup vs baseline: 1.0175x; 1.0025x over previous
; __device__ __forceinline__ float bf_lo(unsigned w) { return __uint_as_float(w << 16); }
; __device__ __forceinline__ float bf_hi(unsigned w) { return __uint_as_float(w & 0xffff0000u); }
; __device__ __forceinline__ void gd_prep_item(CArgs* a, LAS unsigned char* lds, int l, int item) {
;     ...
;             for (int hf = 0; hf < 2; ++hf) { const int d0 = 16 * g + 8 * hf, ch = mat * 1024 + h * 128 + d0; float acc8[8] = {0.f, 0.f, 0.f, 0.f, 0.f, 0.f, 0.f, 0.f};
; #pragma unroll
;                 for (int j = 0; j < 4; ++j) { const int tt = 64 * c + t - 3 + j; u32x4 w = (u32x4){0u, 0u, 0u, 0u};
;                     if (tt >= 0) w = *(const u32x4*)(proj + (size_t)(row0 + t - 3 + j) * NPROJ + PC_GQ + ch);
;                     const float xin[8] = {bf_lo(w.x), bf_hi(w.x), bf_lo(w.y), bf_hi(w.y), bf_lo(w.z), bf_hi(w.z), bf_lo(w.w), bf_hi(w.w)};
;                     if (j == 3 && c == NCH - 1 && t >= 61) { float* op = a->out + O_PGDC + (((size_t)l * NBATCH + b) * 3 + (t - 61)) * 3072 + ch; *(f32x4*)op = (f32x4){xin[0], xin[1], xin[2], xin[3]}; *(f32x4*)(op + 4) = (f32x4){xin[4], xin[5], xin[6], xin[7]}; }
;                     const float* wp = a->in[20] + ((size_t)l * 4 + j) * 3072 + ch; const f32x4 w0 = *(const f32x4*)wp, w1 = *(const f32x4*)(wp + 4);
;                     acc8[0] += w0.x * xin[0]; acc8[1] += w0.y * xin[1]; acc8[2] += w0.z * xin[2]; acc8[3] += w0.w * xin[3]; acc8[4] += w1.x * xin[4]; acc8[5] += w1.y * xin[5]; acc8[6] += w1.z * xin[6]; acc8[7] += w1.w * xin[7]; }
.LBB0_847:
	s_or_b64 exec, exec, s[74:75]
	v_add_co_u32_e32 v22, vcc, 0x3000, v114
	v_lshl_add_u64 v[20:21], v[114:115], 0, s[82:83]
	s_nop 0
	v_addc_co_u32_e32 v23, vcc, 0, v115, vcc
	global_load_dwordx4 v[28:31], v[22:23], off
	s_nop 0
	global_load_dwordx4 v[20:23], v[20:21], off offset:16
	v_mov_b32_e32 v40, 0
	v_lshl_add_u64 v[60:61], v[106:107], 0, v[100:101]
	v_mov_b32_e32 v24, 0
	v_mov_b32_e32 v25, 0
	v_mov_b32_e32 v26, 0
	v_mov_b32_e32 v27, 0
	s_and_saveexec_b64 s[74:75], s[10:11]
	s_cbranch_execz .LBB0_849
	v_add_co_u32_e32 v24, vcc, 0x2b64d000, v60
	s_nop 1
	v_addc_co_u32_e32 v25, vcc, 0, v61, vcc
	global_load_dwordx4 v[24:27], v[24:25], off
.LBB0_849:
	s_or_b64 exec, exec, s[74:75]
	s_mov_b64 s[74:75], 0x6000
	v_add_co_u32_e32 v34, vcc, 0x6000, v114
	v_lshl_add_u64 v[32:33], v[114:115], 0, s[74:75]
	s_nop 0
	v_addc_co_u32_e32 v35, vcc, 0, v115, vcc
	global_load_dwordx4 v[36:39], v[34:35], off
	s_nop 0
	global_load_dwordx4 v[32:35], v[32:33], off offset:16
	v_lshl_add_u64 v[62:63], v[108:109], 0, v[100:101]
	v_mov_b32_e32 v41, 0
	v_mov_b32_e32 v42, 0
	v_mov_b32_e32 v43, 0
	s_and_saveexec_b64 s[74:75], s[12:13]
	s_cbranch_execz .LBB0_851
	v_add_co_u32_e32 v40, vcc, 0x2b64d000, v62
	s_nop 1
	v_addc_co_u32_e32 v41, vcc, 0, v63, vcc
	global_load_dwordx4 v[40:43], v[40:41], off
.LBB0_851:
	s_or_b64 exec, exec, s[74:75]
	s_mov_b64 s[74:75], 0x9000
	v_add_co_u32_e32 v50, vcc, 0x9000, v114
	v_lshl_add_u64 v[48:49], v[114:115], 0, s[74:75]
	s_nop 0
	v_addc_co_u32_e32 v51, vcc, 0, v115, vcc
	global_load_dwordx4 v[52:55], v[50:51], off
	s_nop 0
	global_load_dwordx4 v[48:51], v[48:49], off offset:16
	v_mov_b32_e32 v68, 0
	v_mov_b32_e32 v72, 0
	v_mov_b32_e32 v73, 0
	v_mov_b32_e32 v74, 0
	v_mov_b32_e32 v75, 0
	s_and_saveexec_b64 s[74:75], s[6:7]
	s_cbranch_execz .LBB0_855
	v_add_co_u32_e32 v56, vcc, 0x2b64d000, v56
	s_nop 1
	v_addc_co_u32_e32 v57, vcc, 0, v57, vcc
	global_load_dwordx4 v[72:75], v[56:57], off offset:16

; __device__ __forceinline__ float bf_lo(unsigned w) { return __uint_as_float(w << 16); }
; __device__ __forceinline__ float bf_hi(unsigned w) { return __uint_as_float(w & 0xffff0000u); }
; __device__ __forceinline__ float siluf_(float x) { return x * sigmoidf_(x); }
; __device__ __forceinline__ void gd_prep_item(CArgs* a, LAS unsigned char* lds, int l, int item) {
;     ...
;                 for (int j = 0; j < 4; ++j) { const int tt = 64 * c + t - 3 + j; u32x4 w = (u32x4){0u, 0u, 0u, 0u};
;                     if (tt >= 0) w = *(const u32x4*)(proj + (size_t)(row0 + t - 3 + j) * NPROJ + PC_GQ + ch);
;                     const float xin[8] = {bf_lo(w.x), bf_hi(w.x), bf_lo(w.y), bf_hi(w.y), bf_lo(w.z), bf_hi(w.z), bf_lo(w.w), bf_hi(w.w)};
;                     if (j == 3 && c == NCH - 1 && t >= 61) { float* op = a->out + O_PGDC + (((size_t)l * NBATCH + b) * 3 + (t - 61)) * 3072 + ch; *(f32x4*)op = (f32x4){xin[0], xin[1], xin[2], xin[3]}; *(f32x4*)(op + 4) = (f32x4){xin[4], xin[5], xin[6], xin[7]}; }
;                     const float* wp = a->in[20] + ((size_t)l * 4 + j) * 3072 + ch; const f32x4 w0 = *(const f32x4*)wp, w1 = *(const f32x4*)(wp + 4);
;                     acc8[0] += w0.x * xin[0]; acc8[1] += w0.y * xin[1]; acc8[2] += w0.z * xin[2]; acc8[3] += w0.w * xin[3]; acc8[4] += w1.x * xin[4]; acc8[5] += w1.y * xin[5]; acc8[6] += w1.z * xin[6]; acc8[7] += w1.w * xin[7]; }
; #pragma unroll
;                 for (int j = 0; j < 8; ++j) { const float s = siluf_(acc8[j]); val[8 * hf + j] = s; ssq += s * s; } }
.LBB0_861:
	s_or_b64 exec, exec, s[74:75]
	s_waitcnt vmcnt(0)
	v_lshlrev_b32_e32 v44, 16, v40
	v_and_b32_e32 v45, 0xffff0000, v40
	v_lshlrev_b32_e32 v46, 16, v41
	v_and_b32_e32 v47, 0xffff0000, v41
	v_lshlrev_b32_e32 v40, 16, v42
	v_and_b32_e32 v41, 0xffff0000, v42
	v_lshlrev_b32_e32 v42, 16, v43
	v_and_b32_e32 v43, 0xffff0000, v43
	s_and_saveexec_b64 s[74:75], s[18:19]
	s_cbranch_execz .LBB0_853
	s_load_dwordx2 s[78:79], s[38:39], 0xf0
	s_waitcnt lgkmcnt(0)
	v_lshl_add_u64 v[122:123], s[78:79], 0, v[110:111]
	v_lshl_add_u64 v[122:123], v[122:123], 0, s[40:41]
	v_add_co_u32_e32 v122, vcc, 0x5140000, v122
	s_nop 1
	v_addc_co_u32_e32 v123, vcc, 0, v123, vcc
	global_store_dwordx4 v[122:123], v[44:47], off
	global_store_dwordx4 v[122:123], v[40:43], off offset:16
.LBB0_853:
	s_or_b64 exec, exec, s[74:75]
	v_lshlrev_b32_e32 v60, 16, v56
	v_and_b32_e32 v61, 0xffff0000, v56
	v_lshlrev_b32_e32 v62, 16, v57
	v_and_b32_e32 v63, 0xffff0000, v57
	v_lshlrev_b32_e32 v56, 16, v58
	v_and_b32_e32 v57, 0xffff0000, v58
	v_lshlrev_b32_e32 v58, 16, v59
	v_and_b32_e32 v59, 0xffff0000, v59
	s_and_saveexec_b64 s[74:75], s[18:19]
	s_cbranch_execz .LBB0_863
	s_load_dwordx2 s[78:79], s[38:39], 0xf0
	s_waitcnt lgkmcnt(0)
	v_lshl_add_u64 v[122:123], s[78:79], 0, v[110:111]
	v_lshl_add_u64 v[122:123], v[122:123], 0, s[40:41]
	v_add_co_u32_e32 v122, vcc, 0x5140000, v122
	s_nop 1
	v_addc_co_u32_e32 v123, vcc, 0, v123, vcc
	global_store_dwordx4 v[122:123], v[60:63], off offset:32
	global_store_dwordx4 v[122:123], v[56:59], off offset:48

; #define LAS __attribute__((address_space(3)))
; __device__ __forceinline__ float bf2f(bf16_t v) { return __uint_as_float((unsigned)v << 16); }
; __device__ __forceinline__ float sigmoidf_(float x) { return __builtin_amdgcn_rcpf(1.0f + __builtin_amdgcn_exp2f(-1.4426950408889634f * x)); }
; __device__ __forceinline__ int tid_fresh() { int t = threadIdx.x; asm volatile("" : "+v"(t)); return t; }
; template <bool GD>
; __device__ __forceinline__ void sample_state_item(CArgs* a, LAS unsigned char* lds, int l, int item) {
;     const int tid = tid_fresh(), wave = tid >> 6, lane = tid & 63;
;     const int bb = item >> 3, h = item & 7; const size_t row = (size_t)MP + bb;
;     unsigned char* ws = a->ws; const bf16_t* proj = (const bf16_t*)(ws + WS_PROJ);
;     LAS float* QV = (LAS float*)lds; LAS float* KV = QV + 128; LAS float* VV = KV + 128; LAS float* FV = VV + 128; LAS float* PART = FV + 128;
;     LAS float* RED = (LAS float*)(lds + 4096); LAS float* RED2 = RED + 16 * 128; LAS float* OV = RED2 + 16 * 128;
;     const int dg = tid >> 5, vq = tid & 31;
;     const size_t sidx = (((size_t)l * MS + bb) * NH + h) * HD * HD;
;     const float* Sin = a->in[GD ? 5 : 4] + sidx; float* Sout = a->out + (GD ? O_SGDS : O_SHGS) + sidx;
;     f32x4 S[8];
; #pragma unroll
;     for (int i = 0; i < 8; ++i) S[i] = __builtin_nontemporal_load((const f32x4*)(Sin + (size_t)(dg * 8 + i) * HD + 4 * vq));
;     float eg = 1.f, beta = 0.f;
;     if (!GD) {
;         if (tid < 128) { const int d = tid; const float lb = ((const float*)(ws + WS_LB))[l * 1024 + h * 128 + d];
;             const float sg = sigmoidf_(bf2f(proj[row * NPROJ + PC_HF + h * 128 + d]));
;             FV[d] = lb + (1.0f - lb) * sg; KV[d] = (1.0f - lb) * (1.0f - sg); QV[d] = bf2f(proj[row * NPROJ + PC_HQ + h * 128 + d]) * HSCALE; VV[d] = bf2f(proj[row * NPROJ + PC_HI + h * 128 + d]); }
.LBB0_1171:
	s_add_i32 s41, s38, 0x400
	s_cmpk_gt_i32 s41, 0x7ff
	s_cbranch_scc1 .LBB0_1182
	s_mov_b64 s[16:17], s[0:1]
	v_mov_b32_e32 v40, v0
	s_ashr_i32 s8, s38, 3
	s_ashr_i32 s9, s8, 31
	s_load_dwordx2 s[12:13], s[16:17], 0x20
	s_and_b32 s34, s41, 7
	s_lshl_b64 s[10:11], s[8:9], 3
	s_add_u32 s10, s10, s22
	v_ashrrev_i32_e32 v3, 5, v40
	s_addc_u32 s11, s11, 0
	s_or_b32 s10, s10, s34
	s_lshl_b64 s[14:15], s[10:11], 16
	s_waitcnt vmcnt(0)
	v_lshlrev_b32_e32 v60, 3, v3
	v_lshlrev_b32_e32 v4, 2, v40
	s_waitcnt lgkmcnt(0)
	s_add_u32 s12, s12, s14
	v_and_b32_e32 v4, 0x7c, v4
	v_or_b32_e32 v8, 1, v60
	s_addc_u32 s13, s13, s15
	v_lshlrev_b32_e32 v42, 2, v4
	v_mov_b32_e32 v43, v2
	v_ashrrev_i32_e32 v61, 31, v60
	v_ashrrev_i32_e32 v9, 31, v8
	v_lshl_add_u64 v[4:5], s[12:13], 0, v[42:43]
	v_lshlrev_b64 v[58:59], 9, v[60:61]
	v_lshlrev_b64 v[56:57], 9, v[8:9]
	v_lshl_add_u64 v[6:7], v[4:5], 0, v[58:59]
	v_lshl_add_u64 v[8:9], v[4:5], 0, v[56:57]
	global_load_dwordx4 v[32:35], v[6:7], off nt
	global_load_dwordx4 v[24:27], v[8:9], off nt
	v_or_b32_e32 v6, 2, v60
	v_or_b32_e32 v8, 3, v60
	v_ashrrev_i32_e32 v7, 31, v6
	v_ashrrev_i32_e32 v9, 31, v8
	v_lshlrev_b64 v[54:55], 9, v[6:7]
	v_lshlrev_b64 v[52:53], 9, v[8:9]
	v_lshl_add_u64 v[6:7], v[4:5], 0, v[54:55]
	v_lshl_add_u64 v[8:9], v[4:5], 0, v[52:53]
	global_load_dwordx4 v[28:31], v[6:7], off nt
	global_load_dwordx4 v[20:23], v[8:9], off nt
	v_or_b32_e32 v6, 4, v60
	v_or_b32_e32 v8, 5, v60
	v_ashrrev_i32_e32 v7, 31, v6
	v_ashrrev_i32_e32 v9, 31, v8
	v_lshlrev_b64 v[50:51], 9, v[6:7]
	v_lshlrev_b64 v[48:49], 9, v[8:9]
	v_lshl_add_u64 v[6:7], v[4:5], 0, v[50:51]
	v_lshl_add_u64 v[8:9], v[4:5], 0, v[48:49]
	global_load_dwordx4 v[16:19], v[6:7], off nt
	global_load_dwordx4 v[12:15], v[8:9], off nt
	v_or_b32_e32 v6, 6, v60
	v_or_b32_e32 v8, 7, v60
	v_ashrrev_i32_e32 v7, 31, v6
	v_ashrrev_i32_e32 v9, 31, v8
	v_lshlrev_b64 v[46:47], 9, v[6:7]
	v_lshlrev_b64 v[44:45], 9, v[8:9]
	v_lshl_add_u64 v[6:7], v[4:5], 0, v[46:47]
	v_lshl_add_u64 v[4:5], v[4:5], 0, v[44:45]
	global_load_dwordx4 v[8:11], v[6:7], off nt
	s_nop 0
	global_load_dwordx4 v[4:7], v[4:5], off nt
	s_load_dwordx4 s[12:15], s[16:17], 0xf0
	s_add_u32 s18, s8, 0x2000
	s_addc_u32 s19, s9, 0
	s_movk_i32 s8, 0x80
	v_cmp_gt_i32_e64 s[8:9], s8, v40
	s_waitcnt lgkmcnt(0)
	s_add_u32 s35, s14, 0x2b64a000
	s_addc_u32 s36, s15, 0
	v_ashrrev_i32_e32 v41, 31, v40
	v_lshl_add_u32 v61, v40, 2, 0
	s_and_saveexec_b64 s[30:31], s[8:9]
	s_cbranch_execz .LBB0_1174
	s_lshl_b32 s37, s34, 7
	s_or_b32 s37, s37, s22
	v_add_u32_e32 v36, s37, v40
	s_lshl_b64 s[44:45], s[18:19], 15
	v_ashrrev_i32_e32 v37, 31, v36
	s_add_u32 s37, s35, s44
	v_lshl_add_u64 v[36:37], v[36:37], 2, s[14:15]
	s_addc_u32 s45, s36, s45
	s_lshl_b32 s44, s34, 8
	v_add_co_u32_e32 v36, vcc, 0x100000, v36
	s_add_u32 s44, s37, s44
	s_nop 0
	v_addc_co_u32_e32 v37, vcc, 0, v37, vcc
	s_addc_u32 s45, s45, 0
	global_load_dword v62, v[36:37], off
	v_lshl_add_u64 v[36:37], v[40:41], 1, s[44:45]
	s_movk_i32 s37, 0x1000
	v_add_co_u32_e32 v38, vcc, s37, v36
	s_nop 1
	v_addc_co_u32_e32 v39, vcc, 0, v37, vcc
	global_load_ushort v63, v[38:39], off offset:2048
	v_add_co_u32_e32 v36, vcc, 0x2000, v36
	global_load_ushort v38, v[38:39], off
	s_nop 0
	v_addc_co_u32_e32 v37, vcc, 0, v37, vcc
	global_load_ushort v36, v[36:37], off
	s_waitcnt vmcnt(3)
	v_sub_f32_e32 v64, 1.0, v62
	s_waitcnt vmcnt(2)
	v_lshlrev_b32_e32 v63, 16, v63
	v_mul_f32_e32 v63, 0xbfb8aa3b, v63
	v_exp_f32_e32 v63, v63
	s_waitcnt vmcnt(1)
	v_lshlrev_b32_e32 v38, 16, v38
	v_mul_f32_e32 v38, 0x3db504f3, v38
	v_add_f32_e32 v63, 1.0, v63
	v_rcp_f32_e32 v63, v63
	s_waitcnt vmcnt(0)
	v_lshlrev_b32_e32 v36, 16, v36
	v_fmac_f32_e32 v62, v64, v63
	v_sub_f32_e32 v63, 1.0, v63
	v_mul_f32_e32 v63, v64, v63
	ds_write2st64_b32 v61, v38, v63 offset1:2
	ds_write2st64_b32 v61, v36, v62 offset0:4 offset1:6

; __device__ __forceinline__ float bf2f(bf16_t v) { return __uint_as_float((unsigned)v << 16); }
; __device__ __forceinline__ bf16_t f2bf(float f) { return (bf16_t)(cvt_pk_bf16(f, 0.f) & 0xffffu); }
; __device__ __forceinline__ size_t sfrag(int r, int k) { return ((size_t)(((k >> 5) * 8 + (r >> 4)) * 64 + ((k >> 3) & 3) * 16 + (r & 15))) * 8 + (k & 7); }
; template <bool GD>
; __device__ __forceinline__ void sample_state_item(CArgs* a, LAS unsigned char* lds, int l, int item) {
;     ...
;     float ov = 0.f;
;     if (tid < 128) {
; #pragma unroll
;         for (int g = 0; g < 16; ++g) ov += RED2[g * 128 + tid]; }
;     const float sq = wave_sum(ov * ov);
;     if (lane == 0 && wave < 2) PART[4 + wave] = sq;
;     __syncthreads();
;     if (tid < 128) { const float rstd = __builtin_amdgcn_rsqf((PART[4] + PART[5]) * (1.0f / HD) + EPS);
;         const float gate = bf2f(proj[row * NPROJ + (GD ? PC_GZ : PC_HG) + h * 128 + tid]);
;         ((bf16_t*)(ws + WS_Y + (GD ? 2 : 1) * Y_STRIDE))[(size_t)MP * RGW + sfrag(bb, h * 128 + tid)] = f2bf(ov * rstd * a->in[GD ? 23 : 19][l * 128 + tid] * gate); }
.LBB0_1178:
	s_or_b64 exec, exec, s[10:11]
	s_waitcnt lgkmcnt(0)
	s_barrier
	s_and_saveexec_b64 s[10:11], s[8:9]
	s_cbranch_execz .LBB0_1180
	ds_read_b64 v[4:5], v2 offset:2064
	s_lshl_b64 s[8:9], s[18:19], 15
	s_add_u32 s8, s35, s8
	s_addc_u32 s9, s36, s9
	s_lshl_b32 s12, s34, 8
	s_waitcnt lgkmcnt(0)
	v_add_f32_e32 v4, v4, v5
	s_add_u32 s8, s8, s12
	v_fmamk_f32 v4, v4, 0x3c000000, v1
	s_addc_u32 s9, s9, 0
	v_rsq_f32_e32 v6, v4
	v_lshl_add_u64 v[4:5], v[40:41], 1, s[8:9]
	v_add_co_u32_e32 v4, vcc, s87, v4
	s_load_dwordx2 s[8:9], s[16:17], 0x98
	s_nop 0
	v_addc_co_u32_e32 v5, vcc, 0, v5, vcc
	global_load_ushort v4, v[4:5], off offset:2048
	v_add_u32_e32 v212, s20, v40
	v_ashrrev_i32_e32 v213, 31, v212
	s_waitcnt lgkmcnt(0)
	v_lshl_add_u64 v[212:213], v[212:213], 2, s[8:9]
	global_load_dword v214, v[212:213], off
	v_mul_f32_e32 v3, v3, v6
	v_and_b32_e32 v6, 7, v40
	v_lshlrev_b32_e32 v6, 1, v6
	s_waitcnt vmcnt(0)
	v_lshlrev_b32_e32 v7, 16, v4
	s_ashr_i32 s8, s38, 7
	v_lshlrev_b32_e32 v5, 1, v40
	v_and_b32_e32 v5, 48, v5
	v_mul_f32_e32 v3, v214, v3
	v_lshl_add_u32 v4, s34, 7, v40
	v_lshrrev_b32_e32 v4, 2, v4
	v_and_b32_e32 v4, 0x3fffff8, v4
	v_add_lshl_u32 v4, v4, s8, 6
	s_bfe_u32 s8, s38, 0x40003
	v_or3_b32 v4, v4, v5, s8
	v_ashrrev_i32_e32 v5, 31, v4
	v_mul_f32_e32 v3, v3, v7
	v_lshl_add_u64 v[4:5], v[4:5], 4, s[14:15]
	v_mov_b32_e32 v7, v2
	v_lshl_add_u64 v[4:5], v[4:5], 0, v[6:7]
	v_add_co_u32_e32 v4, vcc, 0x45c8a000, v4
	v_cvt_pk_bf16_f32 v3, v3, s0
	s_nop 0
	v_addc_co_u32_e32 v5, vcc, 0, v5, vcc
	global_store_short v[4:5], v3, off

; __device__ __forceinline__ float bf2f(bf16_t v) { return __uint_as_float((unsigned)v << 16); }
; __device__ __forceinline__ float siluf_(float x) { return x * sigmoidf_(x); }
; template <bool GD>
; __device__ __forceinline__ void sample_state_item(CArgs* a, LAS unsigned char* lds, int l, int item) {
;     ...
;     } else {
;         float val = 0.f;
;         if (tid < 384) { const int mat = tid >> 7, d = tid & 127, ch = mat * 1024 + h * 128 + d;
;             const float pre = bf2f(proj[row * NPROJ + PC_GQ + ch]);
;             const float* cb = a->in[6] + (((size_t)l * MS + bb) * 3) * 3072 + ch; const float b0 = cb[0], b1 = cb[3072], b2 = cb[2 * 3072];
;             float* co = a->out + O_SGDC + (((size_t)l * MS + bb) * 3) * 3072 + ch; co[0] = b1; co[3072] = b2; co[2 * 3072] = pre;
;             const float* cw = a->in[20] + ((size_t)l * 4) * 3072 + ch;
;             val = siluf_(cw[0] * b0 + cw[3072] * b1 + cw[2 * 3072] * b2 + cw[3 * 3072] * pre); }
.LBB0_1183:
	s_mov_b64 s[14:15], s[0:1]
	s_add_i32 s44, s38, 0xfffffc00
	v_mov_b32_e32 v40, v0
	s_lshr_b32 s8, s44, 3
	s_load_dwordx2 s[10:11], s[14:15], 0x28
	s_and_b32 s45, s41, 7
	s_or_b32 s12, s24, s8
	s_mov_b32 s13, s25
	s_lshl_b64 s[16:17], s[12:13], 17
	s_lshl_b32 s9, s45, 14
	s_or_b32 s16, s16, s9
	v_ashrrev_i32_e32 v3, 5, v40
	s_lshl_b64 s[30:31], s[16:17], 2
	v_lshlrev_b32_e32 v5, 2, v40
	s_waitcnt lgkmcnt(0)
	s_add_u32 s10, s10, s30
	v_lshlrev_b32_e32 v4, 3, v3
	v_and_b32_e32 v5, 0x7c, v5
	s_addc_u32 s11, s11, s31
	v_lshlrev_b32_e32 v42, 2, v5
	v_mov_b32_e32 v43, v2
	v_ashrrev_i32_e32 v5, 31, v4
	v_or_b32_e32 v10, 1, v4
	v_lshl_add_u64 v[6:7], s[10:11], 0, v[42:43]
	v_lshlrev_b64 v[58:59], 9, v[4:5]
	v_ashrrev_i32_e32 v11, 31, v10
	v_lshl_add_u64 v[8:9], v[6:7], 0, v[58:59]
	v_lshlrev_b64 v[56:57], 9, v[10:11]
	v_lshl_add_u64 v[10:11], v[6:7], 0, v[56:57]
	global_load_dwordx4 v[32:35], v[8:9], off nt
	global_load_dwordx4 v[24:27], v[10:11], off nt
	v_or_b32_e32 v8, 2, v4
	v_ashrrev_i32_e32 v9, 31, v8
	v_or_b32_e32 v10, 3, v4
	s_waitcnt vmcnt(0)
	v_lshlrev_b64 v[54:55], 9, v[8:9]
	v_ashrrev_i32_e32 v11, 31, v10
	v_lshl_add_u64 v[8:9], v[6:7], 0, v[54:55]
	v_lshlrev_b64 v[52:53], 9, v[10:11]
	v_lshl_add_u64 v[10:11], v[6:7], 0, v[52:53]
	global_load_dwordx4 v[28:31], v[8:9], off nt
	global_load_dwordx4 v[20:23], v[10:11], off nt
	v_or_b32_e32 v8, 4, v4
	v_ashrrev_i32_e32 v9, 31, v8
	v_or_b32_e32 v10, 5, v4
	v_lshlrev_b64 v[50:51], 9, v[8:9]
	v_ashrrev_i32_e32 v11, 31, v10
	v_lshl_add_u64 v[8:9], v[6:7], 0, v[50:51]
	v_lshlrev_b64 v[48:49], 9, v[10:11]
	v_lshl_add_u64 v[10:11], v[6:7], 0, v[48:49]
	global_load_dwordx4 v[16:19], v[8:9], off nt
	global_load_dwordx4 v[12:15], v[10:11], off nt
	v_or_b32_e32 v8, 6, v4
	v_or_b32_e32 v4, 7, v4
	v_ashrrev_i32_e32 v9, 31, v8
	v_ashrrev_i32_e32 v5, 31, v4
	v_lshlrev_b64 v[46:47], 9, v[8:9]
	v_lshlrev_b64 v[44:45], 9, v[4:5]
	v_lshl_add_u64 v[8:9], v[6:7], 0, v[46:47]
	v_lshl_add_u64 v[4:5], v[6:7], 0, v[44:45]
	global_load_dwordx4 v[8:11], v[8:9], off nt
	s_nop 0
	global_load_dwordx4 v[4:7], v[4:5], off nt
	s_load_dwordx4 s[16:19], s[14:15], 0xf0
	s_or_b32 s80, s8, 0x2000
	s_movk_i32 s8, 0x180
	v_cmp_gt_i32_e64 s[10:11], s8, v40
	v_mov_b32_e32 v36, 0
	s_waitcnt lgkmcnt(0)
	s_add_u32 s55, s18, 0x2b64a000
	s_addc_u32 s74, s19, 0
	s_and_saveexec_b64 s[8:9], s[10:11]
	s_cbranch_execz .LBB0_1185
	v_lshlrev_b32_e32 v37, 3, v40
	v_and_b32_e32 v36, 0x7f, v40
	v_and_b32_e32 v37, 0xfffffc00, v37
	s_lshl_b32 s34, s45, 7
	v_or3_b32 v38, v37, s34, v36
	s_lshl_b64 s[34:35], s[80:81], 15
	s_add_u32 s34, s55, s34
	v_ashrrev_i32_e32 v39, 31, v38
	s_addc_u32 s35, s74, s35
	v_lshl_add_u64 v[36:37], v[38:39], 1, s[34:35]
	s_movk_i32 s75, 0x3000
	v_add_co_u32_e32 v36, vcc, s75, v36
	s_load_dwordx2 s[34:35], s[14:15], 0x30
	s_load_dwordx2 s[100:101], s[14:15], 0xa0
	s_nop 0
	v_addc_co_u32_e32 v37, vcc, 0, v37, vcc
	global_load_ushort v36, v[36:37], off
	s_mul_i32 s13, s13, 0x9000
	s_mul_hi_u32 s36, s12, 0x9000
	s_add_i32 s36, s36, s13
	s_mul_i32 s37, s12, 0x9000
	s_waitcnt lgkmcnt(0)
	s_add_u32 s12, s34, s37
	s_addc_u32 s13, s35, s36
	v_lshlrev_b64 v[38:39], 2, v[38:39]
	v_lshl_add_u64 v[60:61], s[12:13], 0, v[38:39]
	v_add_co_u32_e32 v64, vcc, s75, v60
	global_load_dword v62, v[60:61], off
	s_nop 0
	v_addc_co_u32_e32 v65, vcc, 0, v61, vcc
	global_load_dword v63, v[64:65], off
	s_movk_i32 s35, 0x6000
	v_add_co_u32_e32 v60, vcc, s35, v60
	s_add_u32 s12, s16, s37
	s_nop 0
	v_addc_co_u32_e32 v61, vcc, 0, v61, vcc
	s_addc_u32 s13, s17, s36
	s_mul_i32 s34, s96, 0xc000
	global_load_dword v212, v[60:61], off
	s_mul_i32 s36, s96, 0xc000
	s_mul_hi_u32 s37, s96, 0xc000
	s_add_u32 s100, s100, s36
	s_addc_u32 s101, s101, s37
	v_lshl_add_u64 v[216:217], s[100:101], 0, v[38:39]
	global_load_dword v218, v[216:217], off
	s_add_u32 s100, s100, 0x3000
	s_addc_u32 s101, s101, 0
	v_lshl_add_u64 v[216:217], s[100:101], 0, v[38:39]
	global_load_dword v219, v[216:217], off
	s_add_u32 s100, s100, 0x3000
	s_addc_u32 s101, s101, 0
	v_lshl_add_u64 v[216:217], s[100:101], 0, v[38:39]
	global_load_dword v220, v[216:217], off
	s_add_u32 s100, s100, 0x3000
	s_addc_u32 s101, s101, 0
	v_lshl_add_u64 v[216:217], s[100:101], 0, v[38:39]
	global_load_dword v221, v[216:217], off
	s_waitcnt vmcnt(7)
	v_lshlrev_b32_e32 v37, 16, v36
	v_lshl_add_u64 v[60:61], s[12:13], 0, v[38:39]
	s_mov_b32 s12, 0x259d0000
	v_add_co_u32_e32 v64, vcc, s12, v60
	s_mov_b32 s12, 0x259d3000
	s_nop 0
	v_addc_co_u32_e32 v65, vcc, 0, v61, vcc
	s_waitcnt vmcnt(5)
	global_store_dword v[64:65], v63, off
	v_add_co_u32_e32 v64, vcc, s12, v60
	s_mov_b32 s12, 0x259d6000
	s_nop 0
	v_addc_co_u32_e32 v65, vcc, 0, v61, vcc
	v_add_co_u32_e32 v60, vcc, s12, v60
	s_load_dwordx2 s[12:13], s[14:15], 0xa0
	s_nop 0
	v_addc_co_u32_e32 v61, vcc, 0, v61, vcc
	global_store_dword v[60:61], v37, off
	s_waitcnt lgkmcnt(0)
	s_add_u32 s12, s12, s34
	s_mul_hi_u32 s34, s96, 0xc000
	s_addc_u32 s13, s13, s34
	v_lshl_add_u64 v[38:39], s[12:13], 0, v[38:39]
	s_waitcnt vmcnt(6)
	v_mov_b32_e32 v36, v212
	global_store_dword v[64:65], v36, off
	s_waitcnt vmcnt(3)
	v_pk_mul_f32 v[60:61], v[62:63], v[218:219]
	v_add_f32_e32 v38, v60, v61
	v_pk_mul_f32 v[36:37], v[220:221], v[36:37]
	s_nop 0
	v_add_f32_e32 v36, v38, v36
	v_add_f32_e32 v36, v36, v37
	v_mul_f32_e32 v37, 0xbfb8aa3b, v36
	v_exp_f32_e32 v37, v37
	s_nop 0
	v_add_f32_e32 v37, 1.0, v37
	v_rcp_f32_e32 v37, v37
	s_nop 0
	v_mul_f32_e32 v36, v36, v37

; __device__ __forceinline__ float bf2f(bf16_t v) { return __uint_as_float((unsigned)v << 16); }
; __device__ __forceinline__ bf16_t f2bf(float f) { return (bf16_t)(cvt_pk_bf16(f, 0.f) & 0xffffu); }
; __device__ __forceinline__ size_t sfrag(int r, int k) { return ((size_t)(((k >> 5) * 8 + (r >> 4)) * 64 + ((k >> 3) & 3) * 16 + (r & 15))) * 8 + (k & 7); }
; template <bool GD>
; __device__ __forceinline__ void sample_state_item(CArgs* a, LAS unsigned char* lds, int l, int item) {
;     ...
;     float ov = 0.f;
;     if (tid < 128) {
; #pragma unroll
;         for (int g = 0; g < 16; ++g) ov += RED2[g * 128 + tid]; }
;     const float sq = wave_sum(ov * ov);
;     if (lane == 0 && wave < 2) PART[4 + wave] = sq;
;     __syncthreads();
;     if (tid < 128) { const float rstd = __builtin_amdgcn_rsqf((PART[4] + PART[5]) * (1.0f / HD) + EPS);
;         const float gate = bf2f(proj[row * NPROJ + (GD ? PC_GZ : PC_HG) + h * 128 + tid]);
;         ((bf16_t*)(ws + WS_Y + (GD ? 2 : 1) * Y_STRIDE))[(size_t)MP * RGW + sfrag(bb, h * 128 + tid)] = f2bf(ov * rstd * a->in[GD ? 23 : 19][l * 128 + tid] * gate); }
.LBB0_1199:
	s_or_b64 exec, exec, s[10:11]
	s_waitcnt lgkmcnt(0)
	s_barrier
	s_and_saveexec_b64 s[10:11], s[8:9]
	s_cbranch_execz .LBB0_1201
	ds_read_b64 v[4:5], v2 offset:2064
	s_lshl_b64 s[8:9], s[80:81], 15
	s_add_u32 s8, s55, s8
	s_addc_u32 s9, s74, s9
	s_lshl_b32 s12, s45, 8
	s_add_u32 s8, s8, s12
	v_ashrrev_i32_e32 v41, 31, v40
	s_addc_u32 s9, s9, 0
	s_waitcnt lgkmcnt(0)
	v_add_f32_e32 v3, v4, v5
	v_lshl_add_u64 v[4:5], v[40:41], 1, s[8:9]
	s_movk_i32 s8, 0x4000
	v_add_co_u32_e32 v4, vcc, s8, v4
	s_load_dwordx2 s[8:9], s[14:15], 0xb8
	s_nop 0
	v_addc_co_u32_e32 v5, vcc, 0, v5, vcc
	global_load_ushort v4, v[4:5], off offset:2048
	v_add_u32_e32 v212, s20, v40
	v_ashrrev_i32_e32 v213, 31, v212
	s_waitcnt lgkmcnt(0)
	v_lshl_add_u64 v[212:213], v[212:213], 2, s[8:9]
	global_load_dword v214, v[212:213], off
	v_fmamk_f32 v3, v3, 0x3c000000, v1
	v_rsq_f32_e32 v3, v3
	v_mov_b32_e32 v7, v2
	v_mul_f32_e32 v3, v74, v3
	s_waitcnt vmcnt(0)
	v_lshlrev_b32_e32 v6, 16, v4
	s_lshr_b32 s8, s44, 7
	v_lshlrev_b32_e32 v5, 1, v40
	v_and_b32_e32 v5, 48, v5
	v_mul_f32_e32 v3, v214, v3
	v_lshl_add_u32 v4, s45, 7, v40
	v_lshrrev_b32_e32 v4, 2, v4
	v_and_b32_e32 v4, 0x3fffff8, v4
	v_or_b32_e32 v4, s8, v4
	v_lshlrev_b32_e32 v4, 6, v4
	s_bfe_u32 s8, s44, 0x40003
	v_or3_b32 v4, v4, v5, s8
	v_mul_f32_e32 v3, v3, v6
	v_ashrrev_i32_e32 v5, 31, v4
	v_and_b32_e32 v6, 7, v40
	v_lshl_add_u64 v[4:5], v[4:5], 4, s[18:19]
	v_lshlrev_b32_e32 v6, 1, v6
	v_lshl_add_u64 v[4:5], v[4:5], 0, v[6:7]
	v_add_co_u32_e32 v4, vcc, 0x46cca000, v4
	v_cvt_pk_bf16_f32 v3, v3, s0
	s_nop 0
	v_addc_co_u32_e32 v5, vcc, 0, v5, vcc
	global_store_short v[4:5], v3, off
